# attention output stores with sc1 (do not keep o lines in L2)
# baseline (speedup 1.0000x reference)
; __device__ __forceinline__ unsigned cvt_pk_bf16(float lo, float hi) { unsigned r; asm volatile("v_cvt_pk_bf16_f32 %0, %1, %2" : "=v"(r) : "v"(lo), "v"(hi)); return r; }
; __device__ __forceinline__ void attn_item(const Ptrs& P, unsigned char* lds, int b, int tq0, int tid) {
;     ...
;         asm volatile("s_waitcnt lgkmcnt(0)" ::: "memory");
;         if (lane == 0) xa[48 + w] = aseq;
;         while (xa[48 + (w ^ 1)] != aseq) { }
;         const float* pc = (const float*)(stg + (w ^ 1) * 32 * SP);
;         float wa[4], wb[4];
; #pragma unroll
;         for (int j = 0; j < 4; ++j) { const float mo = pc[2048 + j * 64 + lane], lo = pc[2304 + j * 64 + lane];
;             const float mm = fmaxf(mrun[j], mo); const float ea = __expf(mrun[j] - mm), eb = __expf(mo - mm);
;             const float inv = 1.f / (lrun[j] * ea + lo * eb); wa[j] = ea * inv; wb[j] = eb * inv; }
;         bf16_t* op = P.QL + (rowb + tq) * 4096;
; #pragma unroll
;         for (int dt = 0; dt < 8; ++dt)
; #pragma unroll
;             for (int j = 0; j < 4; ++j) { const float v = (half ? oacc[8 + dt][j] : oacc[dt][j]) * wa[j] + pc[(dt * 4 + j) * 64 + lane] * wb[j];
;                 op[(4 * g + j) * 256 + 16 * (8 * half + dt) + r16] = (bf16_t)(cvt_pk_bf16(v, 0.f) & 0xffffu); }
.LBB0_931:
	v_mov_b64_e32 v[0:1], s[20:21]
	ds_read_b32 v0, v0
	s_waitcnt vmcnt(0) lgkmcnt(0)
	v_cmp_eq_u32_e32 vcc, v0, v218
	s_or_b64 s[14:15], vcc, s[14:15]
	s_andn2_b64 exec, exec, s[14:15]
	s_cbranch_execnz .LBB0_931
	s_or_b64 exec, exec, s[14:15]
	s_mulk_i32 s16, 0x4200
	v_add_u32_e32 v8, s16, v203
	ds_read2st64_b32 v[0:1], v8 offset1:32
	v_max_f32_e32 v4, v164, v164
	ds_read2st64_b32 v[2:3], v8 offset0:35 offset1:36
	v_cndmask_b32_e64 v17, v149, v109, s[12:13]
	s_waitcnt lgkmcnt(1)
	v_max_f32_e32 v5, v1, v1
	v_max_f32_e32 v4, v4, v5
	v_sub_f32_e32 v1, v1, v4
	v_sub_f32_e32 v5, v164, v4
	v_mul_f32_e32 v1, 0x3fb8aa3b, v1
	v_mul_f32_e32 v4, 0x3fb8aa3b, v5
	v_exp_f32_e32 v1, v1
	v_exp_f32_e32 v9, v4
	ds_read2st64_b32 v[4:5], v8 offset0:37 offset1:38
	ds_read_b32 v10, v8 offset:9984
	ds_read2st64_b32 v[6:7], v8 offset0:33 offset1:34
	s_waitcnt lgkmcnt(3)
	v_mul_f32_e32 v3, v3, v1
	v_fmac_f32_e32 v3, v191, v9
	v_div_scale_f32 v11, s[14:15], v3, v3, 1.0
	v_rcp_f32_e32 v12, v11
	s_nop 0
	v_fma_f32 v13, -v11, v12, 1.0
	v_fmac_f32_e32 v12, v13, v12
	v_div_scale_f32 v13, vcc, 1.0, v3, 1.0
	v_mul_f32_e32 v14, v13, v12
	v_fma_f32 v15, -v11, v14, v13
	v_fmac_f32_e32 v14, v15, v12
	v_fma_f32 v11, -v11, v14, v13
	s_waitcnt lgkmcnt(0)
	v_max_f32_e32 v13, v6, v6
	v_max_f32_e32 v15, v233, v233
	v_max_f32_e32 v13, v15, v13
	v_sub_f32_e32 v6, v6, v13
	v_sub_f32_e32 v15, v233, v13
	v_mul_f32_e32 v6, 0x3fb8aa3b, v6
	v_mul_f32_e32 v15, 0x3fb8aa3b, v15
	v_exp_f32_e32 v6, v6
	v_exp_f32_e32 v13, v15
	v_div_fmas_f32 v11, v11, v12, v14
	v_div_fixup_f32 v3, v11, v3, 1.0
	v_mul_f32_e32 v4, v4, v6
	v_fmac_f32_e32 v4, v190, v13
	v_div_scale_f32 v12, s[14:15], v4, v4, 1.0
	v_rcp_f32_e32 v14, v12
	v_mul_f32_e32 v9, v9, v3
	v_mul_f32_e32 v3, v1, v3
	v_mul_f32_e32 v0, v0, v3
	v_fma_f32 v1, -v12, v14, 1.0
	v_fmac_f32_e32 v14, v1, v14
	v_div_scale_f32 v1, vcc, 1.0, v4, 1.0
	v_mul_f32_e32 v11, v1, v14
	v_fma_f32 v15, -v12, v11, v1
	v_fmac_f32_e32 v11, v15, v14
	v_fma_f32 v1, -v12, v11, v1
	v_max_f32_e32 v12, v7, v7
	v_max_f32_e32 v15, v234, v234
	v_max_f32_e32 v12, v15, v12
	v_sub_f32_e32 v7, v7, v12
	v_sub_f32_e32 v15, v234, v12
	v_mul_f32_e32 v7, 0x3fb8aa3b, v7
	v_mul_f32_e32 v15, 0x3fb8aa3b, v15
	v_exp_f32_e32 v7, v7
	v_exp_f32_e32 v12, v15
	v_div_fmas_f32 v1, v1, v14, v11
	v_div_fixup_f32 v1, v1, v4, 1.0
	v_mul_f32_e32 v5, v5, v7
	v_fmac_f32_e32 v5, v187, v12
	v_div_scale_f32 v11, s[14:15], v5, v5, 1.0
	v_rcp_f32_e32 v14, v11
	v_mul_f32_e32 v4, v13, v1
	v_mul_f32_e32 v6, v6, v1
	v_fma_f32 v1, -v11, v14, 1.0
	v_fmac_f32_e32 v14, v1, v14
	v_div_scale_f32 v1, vcc, 1.0, v5, 1.0
	v_mul_f32_e32 v13, v1, v14
	v_fma_f32 v15, -v11, v13, v1
	v_fmac_f32_e32 v13, v15, v14
	v_fma_f32 v1, -v11, v13, v1
	v_max_f32_e32 v11, v2, v2
	v_max_f32_e32 v15, v235, v235
	v_max_f32_e32 v11, v15, v11
	v_sub_f32_e32 v2, v2, v11
	v_sub_f32_e32 v15, v235, v11
	v_mul_f32_e32 v2, 0x3fb8aa3b, v2
	v_mul_f32_e32 v15, 0x3fb8aa3b, v15
	v_exp_f32_e32 v2, v2
	v_exp_f32_e32 v11, v15
	v_div_fmas_f32 v1, v1, v14, v13
	v_div_fixup_f32 v1, v1, v5, 1.0
	v_mul_f32_e32 v10, v10, v2
	v_fmac_f32_e32 v10, v186, v11
	v_div_scale_f32 v13, s[14:15], v10, v10, 1.0
	v_rcp_f32_e32 v14, v13
	v_mul_f32_e32 v5, v12, v1
	v_mul_f32_e32 v7, v7, v1
	v_fma_f32 v1, -v13, v14, 1.0
	v_fmac_f32_e32 v14, v1, v14
	v_div_scale_f32 v1, vcc, 1.0, v10, 1.0
	v_mul_f32_e32 v12, v1, v14
	v_fma_f32 v15, -v13, v12, v1
	v_fmac_f32_e32 v12, v15, v14
	v_cndmask_b32_e64 v15, v148, v108, s[12:13]
	v_fmac_f32_e32 v0, v15, v9
	v_cvt_pk_bf16_f32 v15, v0, v165
	ds_read_b32 v16, v8 offset:256
	v_fma_f32 v13, -v13, v12, v1
	v_or_b32_e32 v1, v181, v204
	v_lshlrev_b32_e32 v164, 1, v1
	v_lshl_add_u64 v[0:1], v[184:185], 0, v[164:165]
	global_store_short v[0:1], v15, off sc1
	s_waitcnt lgkmcnt(0)
	v_mul_f32_e32 v15, v6, v16
	v_fmac_f32_e32 v15, v17, v4
	v_cvt_pk_bf16_f32 v15, v15, v165
	ds_read_b32 v16, v8 offset:512
	v_div_fmas_f32 v12, v13, v14, v12
	v_div_fixup_f32 v10, v12, v10, 1.0
	v_cndmask_b32_e64 v12, v150, v110, s[12:13]
	global_store_short v[0:1], v15, off offset:512 sc1
	s_waitcnt lgkmcnt(0)
	v_mul_f32_e32 v13, v7, v16
	v_fmac_f32_e32 v13, v12, v5
	v_cvt_pk_bf16_f32 v12, v13, v165
	ds_read_b32 v13, v8 offset:768
	v_mul_f32_e32 v2, v2, v10
	v_mul_f32_e32 v11, v11, v10
	v_cndmask_b32_e64 v10, v151, v111, s[12:13]
	global_store_short v[0:1], v12, off offset:1024 sc1
	s_waitcnt lgkmcnt(0)
	v_mul_f32_e32 v12, v2, v13
	v_fmac_f32_e32 v12, v10, v11
	v_cvt_pk_bf16_f32 v10, v12, v165
	ds_read_b32 v12, v8 offset:1024
	global_store_short v[0:1], v10, off offset:1536 sc1
	v_cndmask_b32_e64 v10, v136, v100, s[12:13]
	v_cndmask_b32_e64 v13, v137, v101, s[12:13]
	s_waitcnt lgkmcnt(0)
	v_mul_f32_e32 v12, v3, v12
	v_fmac_f32_e32 v12, v10, v9
	v_cvt_pk_bf16_f32 v10, v12, v165
	ds_read_b32 v12, v8 offset:1280
	global_store_short v[0:1], v10, off offset:32 sc1
	s_waitcnt lgkmcnt(0)
	v_mul_f32_e32 v10, v6, v12
	v_fmac_f32_e32 v10, v13, v4
	v_cvt_pk_bf16_f32 v10, v10, v165
	ds_read_b32 v12, v8 offset:1536
	v_cndmask_b32_e64 v13, v138, v102, s[12:13]
	global_store_short v[0:1], v10, off offset:544 sc1
	s_waitcnt lgkmcnt(0)
	v_mul_f32_e32 v10, v7, v12
	v_fmac_f32_e32 v10, v13, v5
	v_cvt_pk_bf16_f32 v10, v10, v165
	ds_read_b32 v12, v8 offset:1792
	v_cndmask_b32_e64 v13, v139, v103, s[12:13]
	global_store_short v[0:1], v10, off offset:1056 sc1
	s_waitcnt lgkmcnt(0)
	v_mul_f32_e32 v10, v2, v12
	v_fmac_f32_e32 v10, v13, v11
	v_cvt_pk_bf16_f32 v10, v10, v165
	ds_read_b32 v12, v8 offset:2048
	global_store_short v[0:1], v10, off offset:1568 sc1
	v_cndmask_b32_e64 v10, v124, v84, s[12:13]
	v_cndmask_b32_e64 v13, v125, v85, s[12:13]
	s_waitcnt lgkmcnt(0)
; __device__ __forceinline__ unsigned cvt_pk_bf16(float lo, float hi) { unsigned r; asm volatile("v_cvt_pk_bf16_f32 %0, %1, %2" : "=v"(r) : "v"(lo), "v"(hi)); return r; }
; __device__ __forceinline__ void attn_item(const Ptrs& P, unsigned char* lds, int b, int tq0, int tid) {
;     ...
;         bf16_t* op = P.QL + (rowb + tq) * 4096;
; #pragma unroll
;         for (int dt = 0; dt < 8; ++dt)
; #pragma unroll
;             for (int j = 0; j < 4; ++j) { const float v = (half ? oacc[8 + dt][j] : oacc[dt][j]) * wa[j] + pc[(dt * 4 + j) * 64 + lane] * wb[j];
;                 op[(4 * g + j) * 256 + 16 * (8 * half + dt) + r16] = (bf16_t)(cvt_pk_bf16(v, 0.f) & 0xffffu); }
	v_mul_f32_e32 v12, v3, v12
	v_fmac_f32_e32 v12, v10, v9
	v_cvt_pk_bf16_f32 v10, v12, v165
	ds_read_b32 v12, v8 offset:2304
	global_store_short v[0:1], v10, off offset:64 sc1
	s_waitcnt lgkmcnt(0)
	v_mul_f32_e32 v10, v6, v12
	v_fmac_f32_e32 v10, v13, v4
	v_cvt_pk_bf16_f32 v10, v10, v165
	ds_read_b32 v12, v8 offset:2560
	v_cndmask_b32_e64 v13, v126, v86, s[12:13]
	global_store_short v[0:1], v10, off offset:576 sc1
	s_waitcnt lgkmcnt(0)
	v_mul_f32_e32 v10, v7, v12
	v_fmac_f32_e32 v10, v13, v5
	v_cvt_pk_bf16_f32 v10, v10, v165
	ds_read_b32 v12, v8 offset:2816
	v_cndmask_b32_e64 v13, v127, v87, s[12:13]
	global_store_short v[0:1], v10, off offset:1088 sc1
	s_waitcnt lgkmcnt(0)
	v_mul_f32_e32 v10, v2, v12
	v_fmac_f32_e32 v10, v13, v11
	v_cvt_pk_bf16_f32 v10, v10, v165
	ds_read_b32 v12, v8 offset:3072
	global_store_short v[0:1], v10, off offset:1600 sc1
	v_cndmask_b32_e64 v10, v112, v68, s[12:13]
	v_cndmask_b32_e64 v13, v113, v69, s[12:13]
	s_waitcnt lgkmcnt(0)
	v_mul_f32_e32 v12, v3, v12
	v_fmac_f32_e32 v12, v10, v9
	v_cvt_pk_bf16_f32 v10, v12, v165
	ds_read_b32 v12, v8 offset:3328
	global_store_short v[0:1], v10, off offset:96 sc1
	s_waitcnt lgkmcnt(0)
	v_mul_f32_e32 v10, v6, v12
	v_fmac_f32_e32 v10, v13, v4
	v_cvt_pk_bf16_f32 v10, v10, v165
	ds_read_b32 v12, v8 offset:3584
	v_cndmask_b32_e64 v13, v114, v70, s[12:13]
	global_store_short v[0:1], v10, off offset:608 sc1
	s_waitcnt lgkmcnt(0)
	v_mul_f32_e32 v10, v7, v12
	v_fmac_f32_e32 v10, v13, v5
	v_cvt_pk_bf16_f32 v10, v10, v165
	ds_read_b32 v12, v8 offset:3840
	v_cndmask_b32_e64 v13, v115, v71, s[12:13]
	global_store_short v[0:1], v10, off offset:1120 sc1
	s_waitcnt lgkmcnt(0)
	v_mul_f32_e32 v10, v2, v12
	v_fmac_f32_e32 v10, v13, v11
	v_cvt_pk_bf16_f32 v10, v10, v165
	ds_read_b32 v12, v8 offset:4096
	global_store_short v[0:1], v10, off offset:1632 sc1
	v_cndmask_b32_e64 v10, v104, v48, s[12:13]
	v_cndmask_b32_e64 v13, v105, v49, s[12:13]
	s_waitcnt lgkmcnt(0)
	v_mul_f32_e32 v12, v3, v12
	v_fmac_f32_e32 v12, v10, v9
	v_cvt_pk_bf16_f32 v10, v12, v165
	ds_read_b32 v12, v8 offset:4352
	global_store_short v[0:1], v10, off offset:128 sc1
	s_waitcnt lgkmcnt(0)
	v_mul_f32_e32 v10, v6, v12
	v_fmac_f32_e32 v10, v13, v4
	v_cvt_pk_bf16_f32 v10, v10, v165
	ds_read_b32 v12, v8 offset:4608
	v_cndmask_b32_e64 v13, v106, v50, s[12:13]
	global_store_short v[0:1], v10, off offset:640 sc1
	s_waitcnt lgkmcnt(0)
	v_mul_f32_e32 v10, v7, v12
	v_fmac_f32_e32 v10, v13, v5
	v_cvt_pk_bf16_f32 v10, v10, v165
	ds_read_b32 v12, v8 offset:4864
	v_cndmask_b32_e64 v13, v107, v51, s[12:13]
	global_store_short v[0:1], v10, off offset:1152 sc1
	s_waitcnt lgkmcnt(0)
	v_mul_f32_e32 v10, v2, v12
	v_fmac_f32_e32 v10, v13, v11
	v_cvt_pk_bf16_f32 v10, v10, v165
	ds_read_b32 v12, v8 offset:5120
	global_store_short v[0:1], v10, off offset:1664 sc1
	v_cndmask_b32_e64 v10, v96, v40, s[12:13]
	v_cndmask_b32_e64 v13, v97, v41, s[12:13]
	s_waitcnt lgkmcnt(0)
	v_mul_f32_e32 v12, v3, v12
	v_fmac_f32_e32 v12, v10, v9
	v_cvt_pk_bf16_f32 v10, v12, v165
	ds_read_b32 v12, v8 offset:5376
	global_store_short v[0:1], v10, off offset:160 sc1
	s_waitcnt lgkmcnt(0)
	v_mul_f32_e32 v10, v6, v12
	v_fmac_f32_e32 v10, v13, v4
	v_cvt_pk_bf16_f32 v10, v10, v165
	ds_read_b32 v12, v8 offset:5632
	v_cndmask_b32_e64 v13, v98, v42, s[12:13]
	global_store_short v[0:1], v10, off offset:672 sc1
	s_waitcnt lgkmcnt(0)
	v_mul_f32_e32 v10, v7, v12
	v_fmac_f32_e32 v10, v13, v5
	v_cvt_pk_bf16_f32 v10, v10, v165
	ds_read_b32 v12, v8 offset:5888
	v_cndmask_b32_e64 v13, v99, v43, s[12:13]
	global_store_short v[0:1], v10, off offset:1184 sc1
	s_waitcnt lgkmcnt(0)
	v_mul_f32_e32 v10, v2, v12
	v_fmac_f32_e32 v10, v13, v11
	v_cvt_pk_bf16_f32 v10, v10, v165
	ds_read_b32 v12, v8 offset:6144
	global_store_short v[0:1], v10, off offset:1696 sc1
	v_cndmask_b32_e64 v10, v80, v36, s[12:13]
	v_cndmask_b32_e64 v13, v81, v37, s[12:13]
	s_waitcnt lgkmcnt(0)
	v_mul_f32_e32 v12, v3, v12
	v_fmac_f32_e32 v12, v10, v9
	v_cvt_pk_bf16_f32 v10, v12, v165
	ds_read_b32 v12, v8 offset:6400
	global_store_short v[0:1], v10, off offset:192 sc1
	s_waitcnt lgkmcnt(0)
	v_mul_f32_e32 v10, v6, v12
	v_fmac_f32_e32 v10, v13, v4
	v_cvt_pk_bf16_f32 v10, v10, v165
	ds_read_b32 v12, v8 offset:6656
	v_cndmask_b32_e64 v13, v82, v38, s[12:13]
	global_store_short v[0:1], v10, off offset:704 sc1
	s_waitcnt lgkmcnt(0)
	v_mul_f32_e32 v10, v7, v12
	v_fmac_f32_e32 v10, v13, v5
	v_cvt_pk_bf16_f32 v10, v10, v165
	ds_read_b32 v12, v8 offset:6912
	v_cndmask_b32_e64 v13, v83, v39, s[12:13]
	global_store_short v[0:1], v10, off offset:1216 sc1
	s_waitcnt lgkmcnt(0)
	v_mul_f32_e32 v10, v2, v12
	v_fmac_f32_e32 v10, v13, v11
	v_cvt_pk_bf16_f32 v10, v10, v165
	ds_read_b32 v12, v8 offset:7168
	global_store_short v[0:1], v10, off offset:1728 sc1
	v_cndmask_b32_e64 v10, v44, v32, s[12:13]
	s_waitcnt lgkmcnt(0)
	v_mul_f32_e32 v3, v3, v12
	v_fmac_f32_e32 v3, v10, v9
	v_cvt_pk_bf16_f32 v3, v3, v165
	ds_read_b32 v9, v8 offset:7424
	v_cndmask_b32_e64 v10, v45, v33, s[12:13]
	global_store_short v[0:1], v3, off offset:224 sc1
	s_waitcnt lgkmcnt(0)
	v_mul_f32_e32 v3, v6, v9
	v_fmac_f32_e32 v3, v10, v4
	v_cvt_pk_bf16_f32 v3, v3, v165
	ds_read_b32 v4, v8 offset:7680
	v_cndmask_b32_e64 v6, v46, v34, s[12:13]
	global_store_short v[0:1], v3, off offset:736 sc1
	s_waitcnt lgkmcnt(0)
	v_mul_f32_e32 v3, v7, v4
	v_fmac_f32_e32 v3, v6, v5
	v_cvt_pk_bf16_f32 v3, v3, v165
	ds_read_b32 v4, v8 offset:7936
	v_cndmask_b32_e64 v5, v47, v35, s[12:13]
	s_xor_b64 s[12:13], exec, -1
	global_store_short v[0:1], v3, off offset:1248 sc1
	s_waitcnt lgkmcnt(0)
	v_mul_f32_e32 v2, v2, v4
	v_fmac_f32_e32 v2, v5, v11
	v_cvt_pk_bf16_f32 v2, v2, v165
	global_store_short v[0:1], v2, off offset:1760 sc1
	s_branch .Lq_next
